# indexer loop v4 (barrier between steps, all work in MFMA gaps) + P2a batched window loads + P2b k/v loads hoisted
# speedup vs baseline: 1.0757x; 1.0379x over previous
; #define LAS __attribute__((address_space(3)))
; __device__ __forceinline__ float bf_lo(unsigned v) { return __uint_as_float(v << 16); }
; __device__ __forceinline__ float bf_hi(unsigned v) { return __uint_as_float(v & 0xffff0000u); }
; __device__ __forceinline__ int lane_id() { int l; asm volatile("v_mbcnt_lo_u32_b32 %0, -1, 0\n\tv_mbcnt_hi_u32_b32 %0, -1, %0\n\ts_nop 1" : "=v"(l)); return l; }
; __device__ __forceinline__ void indexer_block16(const bf16_t* __restrict__ Z, const bf16_t* __restrict__ KI, int* __restrict__ SEL, int qb, LAS unsigned char* lds, int wave) {
;     const int lane = lane_id(), tid = wave * 64 + lane, half = lane >> 5, r = lane & 31;
;     LAS u32x2* wbuf = (LAS u32x2*)lds + wave * 1536;
;     LAS unsigned char* tiles = lds + 98304;
;     LAS int* flags = (LAS int*)(lds + 98304 + 32768);
;     const int tA = qb * 16 + wave * 2, tmine = tA + half;
;     bf16x8 Af[4];
;     { const int aq = tA + ((r >> 2) & 1), ah = (r >> 3) * 4 + (r & 3);
;       const bf16_t* ap = Z + (size_t)aq * ZLD + OFF_QI + ah * 64 + half * 8;
; #pragma unroll
;       for (int kk = 0; kk < 4; ++kk) Af[kk] = *(const bf16x8*)(ap + kk * 16); }
;     float wq[16];
;     { const u32x4* wp = (const u32x4*)(Z + (size_t)tmine * ZLD + OFF_WI); const u32x4 a = wp[0], b = wp[1];
;       wq[0] = bf_lo(a.x); wq[1] = bf_hi(a.x); wq[2] = bf_lo(a.y); wq[3] = bf_hi(a.y); wq[4] = bf_lo(a.z); wq[5] = bf_hi(a.z); wq[6] = bf_lo(a.w); wq[7] = bf_hi(a.w);
;       wq[8] = bf_lo(b.x); wq[9] = bf_hi(b.x); wq[10] = bf_lo(b.y); wq[11] = bf_hi(b.y); wq[12] = bf_lo(b.z); wq[13] = bf_hi(b.z); wq[14] = bf_lo(b.w); wq[15] = bf_hi(b.w);
; #pragma unroll
;       for (int i = 0; i < 16; ++i) wq[i] *= 0.03125f; }
;     const int ntiles = (qb * 16 + 16 + 127) >> 7;
;     float tau = -__builtin_inff(); int cntA = 0, cntB = 0;
;     const u32x4* gsrc = (const u32x4*)KI + tid;
;     { const u32x4 g0 = gsrc[0], g1 = gsrc[512]; *(LAS u32x4*)(tiles + tid * 16) = g0; *(LAS u32x4*)(tiles + 8192 + tid * 16) = g1; }
;     __syncthreads();
.Lidx_pass:
	v_mbcnt_lo_u32_b32 v100, -1, 0
	v_mbcnt_hi_u32_b32 v100, -1, v100
	s_nop 1
	s_add_i32 s92, s49, s72
	v_lshrrev_b32_e32 v0, 2, v100
	v_and_or_b32 v2, v0, 1, s92
	v_lshrrev_b32_e32 v0, 1, v100
	v_and_b32_e32 v1, 3, v100
	v_ashrrev_i32_e32 v8, 5, v100
	v_and_or_b32 v4, v0, 12, v1
	v_mov_b64_e32 v[0:1], s[42:43]
	v_mad_i64_i32 v[2:3], s[4:5], v2, s81, v[0:1]
	v_lshlrev_b32_e32 v90, 7, v4
	v_lshlrev_b32_e32 v4, 3, v8
	v_lshl_add_u64 v[2:3], v[2:3], 0, v[90:91]
	v_ashrrev_i32_e32 v5, 31, v4
	v_lshl_add_u64 v[2:3], v[4:5], 1, v[2:3]
	v_lshl_add_u64 v[18:19], v[2:3], 0, s[84:85]
	v_add_co_u32_e32 v2, vcc, s83, v2
	v_add_u32_e32 v90, s92, v8
	s_nop 0
	v_addc_co_u32_e32 v3, vcc, 0, v3, vcc
	v_mad_i64_i32 v[0:1], s[4:5], v90, s81, v[0:1]
	v_add_u32_e32 v20, s33, v100
	v_add_co_u32_e32 v4, vcc, s83, v0
	v_ashrrev_i32_e32 v21, 31, v20
	s_nop 0
	v_addc_co_u32_e32 v5, vcc, 0, v1, vcc
	v_lshl_add_u64 v[102:103], v[20:21], 4, s[56:57]
	v_add_co_u32_e32 v10, vcc, s83, v102
	v_lshl_add_u64 v[0:1], v[0:1], 0, s[88:89]
	s_nop 0
	v_addc_co_u32_e32 v11, vcc, 0, v103, vcc
	global_load_dwordx4 v[4:7], v[4:5], off offset:2176
	s_nop 0
	global_load_dwordx4 v[10:13], v[10:11], off
	s_nop 0
	global_load_dwordx4 v[64:67], v[18:19], off offset:32
	global_load_dwordx4 v[14:17], v[102:103], off
	global_load_dwordx4 v[68:71], v[18:19], off offset:64
	global_load_dwordx4 v[72:75], v[18:19], off offset:96
	global_load_dwordx4 v[76:79], v[2:3], off
	s_nop 0
	global_load_dwordx4 v[0:3], v[0:1], off offset:16
	s_add_i32 s4, s49, 0x8f
	s_ashr_i32 s93, s4, 7
	v_lshl_add_u32 v9, v20, 4, 0
	s_mov_b32 s74, 0
	v_add_u32_e32 v101, 0x18000, v9
	v_add_u32_e32 v9, 0x1a000, v9
	s_cmp_lt_i32 s93, 1
	s_mov_b32 s75, 0
	s_waitcnt vmcnt(6)
	ds_write_b128 v9, v[10:13]
	s_waitcnt vmcnt(4)
	ds_write_b128 v101, v[14:17]
	s_waitcnt lgkmcnt(0)
	s_barrier
	s_cbranch_scc1 .LBB0_573
	s_waitcnt vmcnt(0)
	v_lshlrev_b32_e32 v14, 16, v0
	v_and_b32_e32 v15, 0xffff0000, v0
	v_lshlrev_b32_e32 v0, 16, v1
	v_and_b32_e32 v1, 0xffff0000, v1
	v_pk_mul_f32 v[114:115], v[0:1], s[90:91] op_sel_hi:[1,0]
	s_add_i32 s4, 0, 0x18000
	v_mul_lo_u32 v0, v8, s79
	v_lshlrev_b32_e32 v10, 16, v4
	v_and_b32_e32 v11, 0xffff0000, v4
	v_lshlrev_b32_e32 v4, 16, v5
	v_and_b32_e32 v5, 0xffff0000, v5
	v_lshlrev_b32_e32 v12, 16, v6
	v_and_b32_e32 v13, 0xffff0000, v6
	v_lshlrev_b32_e32 v6, 16, v7
	v_and_b32_e32 v7, 0xffff0000, v7
	v_lshlrev_b32_e32 v16, 16, v2
	v_and_b32_e32 v17, 0xffff0000, v2
	v_lshlrev_b32_e32 v2, 16, v3
	v_and_b32_e32 v3, 0xffff0000, v3
	v_lshl_add_u32 v125, v100, 4, s4
	v_add_u32_e32 v126, s97, v0
	v_and_b32_e32 v0, 7, v100
	s_add_i32 s4, 0, 0x20000
	v_and_b32_e32 v124, 31, v100
	v_pk_mul_f32 v[104:105], v[10:11], s[90:91] op_sel_hi:[1,0]
	v_pk_mul_f32 v[106:107], v[4:5], s[90:91] op_sel_hi:[1,0]
	v_pk_mul_f32 v[108:109], v[12:13], s[90:91] op_sel_hi:[1,0]
	v_pk_mul_f32 v[110:111], v[6:7], s[90:91] op_sel_hi:[1,0]
	v_pk_mul_f32 v[112:113], v[14:15], s[90:91] op_sel_hi:[1,0]
	v_pk_mul_f32 v[116:117], v[16:17], s[90:91] op_sel_hi:[1,0]
	v_pk_mul_f32 v[118:119], v[2:3], s[90:91] op_sel_hi:[1,0]
	v_cmp_gt_u32_e64 s[6:7], 32, v100
	v_cmp_lt_u32_e64 s[8:9], 31, v100
	v_cmp_eq_u32_e64 s[10:11], 0, v100
	v_lshl_add_u32 v127, v0, 2, s4
	v_mov_b32_e32 v128, 0xff800000
	s_mov_b32 s12, 0
	s_lshl_b32 s32, s33, 4
	s_add_i32 s32, s32, 0x18000
	v_add_u32_e32 v221, s33, v100
	v_lshlrev_b32_e32 v221, 4, v221
	v_add_u32_e32 v222, 0x2000, v221
	s_mov_b32 s95, 0
	v_mov_b32_e32 v219, v125
	v_mov_b32_e32 v223, v124
	v_mov_b32_e32 v218, s91
	v_mov_b32_e32 v224, v127
	s_add_u32 s100, s56, 0x4000
	s_addc_u32 s101, s57, 0
	s_cmp_lt_i32 s93, 2
	s_cbranch_scc1 .Lidx_nodma1
	s_add_i32 m0, s32, 0x4000
	s_nop 0
	global_load_lds_dwordx4 v221, s[100:101]
	s_add_i32 m0, s32, 0x6000
	s_nop 0
	global_load_lds_dwordx4 v222, s[100:101]
.Lidx_nodma1:
	s_add_u32 s100, s100, 0x4000
	s_addc_u32 s101, s101, 0
	ds_read_b128 v[180:183], v219 offset:0
	ds_read_b128 v[184:187], v219 offset:1024
	ds_read_b128 v[188:191], v219 offset:2048
	ds_read_b128 v[192:195], v219 offset:3072
	ds_read_b128 v[196:199], v219 offset:4096
	ds_read_b128 v[200:203], v219 offset:5120
	ds_read_b128 v[204:207], v219 offset:6144
	ds_read_b128 v[208:211], v219 offset:7168
	s_waitcnt lgkmcnt(4)
	v_mfma_f32_32x32x16_bf16 v[148:163], v[76:79], v[180:183], 0
	v_mfma_f32_32x32x16_bf16 v[148:163], v[64:67], v[184:187], v[148:163]
	v_mfma_f32_32x32x16_bf16 v[148:163], v[68:71], v[188:191], v[148:163]
	v_mfma_f32_32x32x16_bf16 v[148:163], v[72:75], v[192:195], v[148:163]
	s_nop 7
	s_nop 3
	s_cmp_lt_i32 s93, 2
	s_cbranch_scc1 .Lidx_last
; __device__ __forceinline__ void indexer_block16(const bf16_t* __restrict__ Z, const bf16_t* __restrict__ KI, int* __restrict__ SEL, int qb, LAS unsigned char* lds, int wave) {
;     ...
;         for (int st = 0; st < 4; ++st) {
;             bf16x8 Bc[4];
; #pragma unroll
;             for (int kk = 0; kk < 4; ++kk) Bc[kk] = *(const LAS bf16x8*)(tb + (st * 4 + kk) * 1024);
;             f32x16 acc = {0.f, 0.f, 0.f, 0.f, 0.f, 0.f, 0.f, 0.f, 0.f, 0.f, 0.f, 0.f, 0.f, 0.f, 0.f, 0.f};
; #pragma unroll
;             for (int kk = 0; kk < 4; ++kk) acc = __builtin_amdgcn_mfma_f32_32x32x16_bf16(Af[kk], Bc[kk], acc, 0, 0, 0);
;             float s0 = 0.f, s1 = 0.f;
; #pragma unroll
;             for (int h = 0; h < 16; h += 2) { const int b0 = __float_as_int(acc[h]), b1 = __float_as_int(acc[h + 1]);
;                 s0 = fmaf(wq[h], __int_as_float(b0 > 0 ? b0 : 0), s0); s1 = fmaf(wq[h + 1], __int_as_float(b1 > 0 ? b1 : 0), s1); }
;             sc[st] = s0 + s1;
;     ...
;             { f32x16 acc2 = {0.f, 0.f, 0.f, 0.f, 0.f, 0.f, 0.f, 0.f, 0.f, 0.f, 0.f, 0.f, 0.f, 0.f, 0.f, 0.f};
; #pragma unroll
;               for (int kk = 0; kk < 4; ++kk) acc2 = __builtin_amdgcn_mfma_f32_32x32x16_bf16(Af[kk], Bc[3 - kk], acc2, 0, 0, 0);
;               float t0 = 0.f, t1 = 0.f;
; #pragma unroll
;               for (int h = 0; h < 16; h += 2) { const int b0 = __float_as_int(acc2[h]), b1 = __float_as_int(acc2[h + 1]);
;                   t0 = fmaf(wq[h], __int_as_float(b0 > 0 ? b0 : 0), t0); t1 = fmaf(wq[h + 1], __int_as_float(b1 > 0 ? b1 : 0), t1); }
;               asm volatile("" :: "v"(t0 + t1)); }
;     ...
;         }
; #pragma unroll
;         for (int st = 0; st < 4; ++st) {
;             const int key = i * 128 + st * 32 + r;
;             const bool pass = (key <= tmine) && (sc[st] > tau);
;             const unsigned long long mk = __builtin_amdgcn_ballot_w64(pass);
;             if (mk != 0ull) {
;                 const unsigned lo = (unsigned)mk, hi = (unsigned)(mk >> 32);
;                 const int pre = half ? __builtin_amdgcn_mbcnt_hi(hi, 0) : __builtin_amdgcn_mbcnt_lo(lo, 0);
;                 const int base = half ? cntB : cntA;
;                 if (pass) { u32x2 o; o.x = __float_as_uint(sc[st]); o.y = (unsigned)key; wbuf[half * 768 + base + pre] = o; }
;                 cntA += __builtin_popcount(lo); cntB += __builtin_popcount(hi);
;             }
;         }
.Lidx_tile:
	ds_read_b128 v[180:183], v219 offset:8192
	ds_read_b128 v[184:187], v219 offset:9216
	s_waitcnt lgkmcnt(2)
	v_mfma_f32_32x32x16_bf16 v[164:179], v[76:79], v[196:199], 0
	ds_read_b128 v[188:191], v219 offset:10240
	ds_read_b128 v[192:195], v219 offset:11264
	v_max_i32_e32 v148, 0, v148
	v_max_i32_e32 v149, 0, v149
	v_fma_f32 v212, v104, v148, 0
	v_fma_f32 v214, v105, v149, 0
	v_max_i32_e32 v150, 0, v150
	v_max_i32_e32 v151, 0, v151
	v_fmac_f32_e32 v212, v106, v150
	v_fmac_f32_e32 v214, v107, v151
	v_max_i32_e32 v152, 0, v152
	v_max_i32_e32 v153, 0, v153
	v_fmac_f32_e32 v212, v108, v152
	v_fmac_f32_e32 v214, v109, v153
	v_mfma_f32_32x32x16_bf16 v[164:179], v[64:67], v[200:203], v[164:179]
	v_max_i32_e32 v154, 0, v154
	v_max_i32_e32 v155, 0, v155
	v_fmac_f32_e32 v212, v110, v154
	v_fmac_f32_e32 v214, v111, v155
	v_max_i32_e32 v156, 0, v156
	v_max_i32_e32 v157, 0, v157
	v_fmac_f32_e32 v212, v112, v156
	v_fmac_f32_e32 v214, v113, v157
	v_max_i32_e32 v158, 0, v158
	v_max_i32_e32 v159, 0, v159
	v_fmac_f32_e32 v212, v114, v158
	v_fmac_f32_e32 v214, v115, v159
	v_mfma_f32_32x32x16_bf16 v[164:179], v[68:71], v[204:207], v[164:179]
	v_max_i32_e32 v160, 0, v160
	v_max_i32_e32 v161, 0, v161
	v_fmac_f32_e32 v212, v116, v160
	v_fmac_f32_e32 v214, v117, v161
	v_max_i32_e32 v162, 0, v162
	v_max_i32_e32 v163, 0, v163
	v_fmac_f32_e32 v212, v118, v162
	v_fmac_f32_e32 v214, v119, v163
	v_add_f32_e32 v212, v212, v214
	v_cmp_gt_f32_e32 vcc, v212, v128
	v_mov_b32_e32 v213, v223
	s_bcnt1_i32_b32 s4, vcc_lo
	s_bcnt1_i32_b32 s5, vcc_hi
	v_mbcnt_lo_u32_b32 v215, vcc_lo, 0
	v_mfma_f32_32x32x16_bf16 v[164:179], v[72:75], v[208:211], v[164:179]
	v_mbcnt_hi_u32_b32 v216, vcc_hi, 0
	v_add_lshl_u32 v215, v215, s74, 3
	v_add_lshl_u32 v216, v216, s75, 3
	v_cndmask_b32_e64 v215, v216, v215, s[6:7]
	v_add_u32_e32 v215, v126, v215
	s_mov_b64 exec, vcc
	ds_write_b64 v215, v[212:213]
	s_mov_b64 exec, -1
	s_add_i32 s74, s74, s4
	s_add_i32 s75, s75, s5
	ds_read_b128 v[196:199], v219 offset:12288
	ds_read_b128 v[200:203], v219 offset:13312
	s_waitcnt lgkmcnt(2)
	v_mfma_f32_32x32x16_bf16 v[148:163], v[76:79], v[180:183], 0
	ds_read_b128 v[204:207], v219 offset:14336
	ds_read_b128 v[208:211], v219 offset:15360
	v_max_i32_e32 v164, 0, v164
	v_max_i32_e32 v165, 0, v165
	v_fma_f32 v212, v104, v164, 0
	v_fma_f32 v214, v105, v165, 0
	v_max_i32_e32 v166, 0, v166
	v_max_i32_e32 v167, 0, v167
	v_fmac_f32_e32 v212, v106, v166
	v_fmac_f32_e32 v214, v107, v167
	v_max_i32_e32 v168, 0, v168
	v_max_i32_e32 v169, 0, v169
	v_fmac_f32_e32 v212, v108, v168
	v_fmac_f32_e32 v214, v109, v169
	v_mfma_f32_32x32x16_bf16 v[148:163], v[64:67], v[184:187], v[148:163]
	v_max_i32_e32 v170, 0, v170
	v_max_i32_e32 v171, 0, v171
	v_fmac_f32_e32 v212, v110, v170
	v_fmac_f32_e32 v214, v111, v171
	v_max_i32_e32 v172, 0, v172
	v_max_i32_e32 v173, 0, v173
	v_fmac_f32_e32 v212, v112, v172
	v_fmac_f32_e32 v214, v113, v173
	v_max_i32_e32 v174, 0, v174
	v_max_i32_e32 v175, 0, v175
	v_fmac_f32_e32 v212, v114, v174
	v_fmac_f32_e32 v214, v115, v175
	v_mfma_f32_32x32x16_bf16 v[148:163], v[68:71], v[188:191], v[148:163]
	v_max_i32_e32 v176, 0, v176
	v_max_i32_e32 v177, 0, v177
	v_fmac_f32_e32 v212, v116, v176
	v_fmac_f32_e32 v214, v117, v177
	v_max_i32_e32 v178, 0, v178
	v_max_i32_e32 v179, 0, v179
	v_fmac_f32_e32 v212, v118, v178
	v_fmac_f32_e32 v214, v119, v179
	v_add_f32_e32 v212, v212, v214
	v_cmp_gt_f32_e32 vcc, v212, v128
	v_or_b32_e32 v213, 32, v223
	s_bcnt1_i32_b32 s4, vcc_lo
	s_bcnt1_i32_b32 s5, vcc_hi
	s_add_i32 s12, s74, s4
	s_add_i32 s13, s75, s5
	s_max_i32 s12, s12, s13
	s_cmpk_gt_i32 s12, 0x280
	s_cselect_b32 s12, 1, 0
	v_mov_b32_e32 v217, s12
	s_mov_b64 exec, 1
	ds_write_b32 v218, v217
	s_mov_b64 exec, -1
	v_mfma_f32_32x32x16_bf16 v[148:163], v[72:75], v[192:195], v[148:163]
	v_mbcnt_lo_u32_b32 v215, vcc_lo, 0
	v_mbcnt_hi_u32_b32 v216, vcc_hi, 0
	v_add_lshl_u32 v215, v215, s74, 3
	v_add_lshl_u32 v216, v216, s75, 3
	v_cndmask_b32_e64 v215, v216, v215, s[6:7]
	v_add_u32_e32 v215, v126, v215
	s_mov_b64 exec, vcc
	ds_write_b64 v215, v[212:213]
	s_mov_b64 exec, -1
	s_add_i32 s74, s74, s4
	s_add_i32 s75, s75, s5
	v_xor_b32_e32 v220, 0x4000, v219
	s_waitcnt vmcnt(0) lgkmcnt(0)
	s_barrier
	v_mfma_f32_32x32x16_bf16 v[164:179], v[76:79], v[196:199], 0
	ds_read_b32 v217, v224
	ds_read_b128 v[180:183], v220 offset:0
	ds_read_b128 v[184:187], v220 offset:1024
	ds_read_b128 v[188:191], v220 offset:2048
	ds_read_b128 v[192:195], v220 offset:3072
	v_max_i32_e32 v148, 0, v148
	v_max_i32_e32 v149, 0, v149
	v_fma_f32 v226, v104, v148, 0
	v_fma_f32 v228, v105, v149, 0
	v_max_i32_e32 v150, 0, v150
	v_max_i32_e32 v151, 0, v151
	v_mfma_f32_32x32x16_bf16 v[164:179], v[64:67], v[200:203], v[164:179]
	s_add_i32 s16, s95, 2
	s_cmp_ge_i32 s16, s93
	s_cbranch_scc1 .Lidx_nodma
	s_and_b32 s17, s95, 1
	s_lshl_b32 s17, s17, 14
	s_add_i32 s17, s17, s32
	s_mov_b32 m0, s17
	s_nop 0
	global_load_lds_dwordx4 v221, s[100:101]
	s_add_i32 m0, s17, 0x2000
	s_nop 0
	global_load_lds_dwordx4 v222, s[100:101]
	s_add_u32 s100, s100, 0x4000
	s_addc_u32 s101, s101, 0
; __device__ __forceinline__ void indexer_block16(const bf16_t* __restrict__ Z, const bf16_t* __restrict__ KI, int* __restrict__ SEL, int qb, LAS unsigned char* lds, int wave) {
;     ...
;         for (int st = 0; st < 4; ++st) {
;             bf16x8 Bc[4];
; #pragma unroll
;             for (int kk = 0; kk < 4; ++kk) Bc[kk] = *(const LAS bf16x8*)(tb + (st * 4 + kk) * 1024);
;             f32x16 acc = {0.f, 0.f, 0.f, 0.f, 0.f, 0.f, 0.f, 0.f, 0.f, 0.f, 0.f, 0.f, 0.f, 0.f, 0.f, 0.f};
; #pragma unroll
;             for (int kk = 0; kk < 4; ++kk) acc = __builtin_amdgcn_mfma_f32_32x32x16_bf16(Af[kk], Bc[kk], acc, 0, 0, 0);
;             float s0 = 0.f, s1 = 0.f;
; #pragma unroll
;             for (int h = 0; h < 16; h += 2) { const int b0 = __float_as_int(acc[h]), b1 = __float_as_int(acc[h + 1]);
;                 s0 = fmaf(wq[h], __int_as_float(b0 > 0 ? b0 : 0), s0); s1 = fmaf(wq[h + 1], __int_as_float(b1 > 0 ? b1 : 0), s1); }
;             sc[st] = s0 + s1;
;     ...
;             { f32x16 acc2 = {0.f, 0.f, 0.f, 0.f, 0.f, 0.f, 0.f, 0.f, 0.f, 0.f, 0.f, 0.f, 0.f, 0.f, 0.f, 0.f};
; #pragma unroll
;               for (int kk = 0; kk < 4; ++kk) acc2 = __builtin_amdgcn_mfma_f32_32x32x16_bf16(Af[kk], Bc[3 - kk], acc2, 0, 0, 0);
;               float t0 = 0.f, t1 = 0.f;
; #pragma unroll
;               for (int h = 0; h < 16; h += 2) { const int b0 = __float_as_int(acc2[h]), b1 = __float_as_int(acc2[h + 1]);
;                   t0 = fmaf(wq[h], __int_as_float(b0 > 0 ? b0 : 0), t0); t1 = fmaf(wq[h + 1], __int_as_float(b1 > 0 ? b1 : 0), t1); }
;               asm volatile("" :: "v"(t0 + t1)); }
;     ...
;         }
; #pragma unroll
;         for (int st = 0; st < 4; ++st) {
;             const int key = i * 128 + st * 32 + r;
;             const bool pass = (key <= tmine) && (sc[st] > tau);
;             const unsigned long long mk = __builtin_amdgcn_ballot_w64(pass);
;             if (mk != 0ull) {
;                 const unsigned lo = (unsigned)mk, hi = (unsigned)(mk >> 32);
;                 const int pre = half ? __builtin_amdgcn_mbcnt_hi(hi, 0) : __builtin_amdgcn_mbcnt_lo(lo, 0);
;                 const int base = half ? cntB : cntA;
;                 if (pass) { u32x2 o; o.x = __float_as_uint(sc[st]); o.y = (unsigned)key; wbuf[half * 768 + base + pre] = o; }
;                 cntA += __builtin_popcount(lo); cntB += __builtin_popcount(hi);
;             }
;         }
.Lidx_nodma:
	v_fmac_f32_e32 v226, v106, v150
	v_fmac_f32_e32 v228, v107, v151
	v_max_i32_e32 v152, 0, v152
	v_max_i32_e32 v153, 0, v153
	v_fmac_f32_e32 v226, v108, v152
	v_fmac_f32_e32 v228, v109, v153
	v_mfma_f32_32x32x16_bf16 v[164:179], v[68:71], v[204:207], v[164:179]
	v_max_i32_e32 v154, 0, v154
	v_max_i32_e32 v155, 0, v155
	v_fmac_f32_e32 v226, v110, v154
	v_fmac_f32_e32 v228, v111, v155
	v_max_i32_e32 v156, 0, v156
	v_max_i32_e32 v157, 0, v157
	v_fmac_f32_e32 v226, v112, v156
	v_fmac_f32_e32 v228, v113, v157
	v_max_i32_e32 v158, 0, v158
	v_max_i32_e32 v159, 0, v159
	v_fmac_f32_e32 v226, v114, v158
	v_fmac_f32_e32 v228, v115, v159
	s_waitcnt lgkmcnt(4)
	v_cmp_ne_u32_e64 s[14:15], 0, v217
	v_mfma_f32_32x32x16_bf16 v[164:179], v[72:75], v[208:211], v[164:179]
	v_max_i32_e32 v160, 0, v160
	v_max_i32_e32 v161, 0, v161
	v_fmac_f32_e32 v226, v116, v160
	v_fmac_f32_e32 v228, v117, v161
	v_max_i32_e32 v162, 0, v162
	v_max_i32_e32 v163, 0, v163
	v_fmac_f32_e32 v226, v118, v162
	v_fmac_f32_e32 v228, v119, v163
	v_add_f32_e32 v226, v226, v228
	v_xor_b32_e32 v218, 32, v218
	v_xor_b32_e32 v224, 32, v224
	s_cmp_lg_u64 s[14:15], 0
	s_cbranch_scc1 .Lidx_compact
.LBB0_571:
	ds_read_b128 v[196:199], v220 offset:4096
	ds_read_b128 v[200:203], v220 offset:5120
	s_waitcnt lgkmcnt(2)
	v_mfma_f32_32x32x16_bf16 v[148:163], v[76:79], v[180:183], 0
	ds_read_b128 v[204:207], v220 offset:6144
	ds_read_b128 v[208:211], v220 offset:7168
	v_cmp_gt_f32_e32 vcc, v226, v128
	v_or_b32_e32 v227, 64, v223
	s_bcnt1_i32_b32 s4, vcc_lo
	s_bcnt1_i32_b32 s5, vcc_hi
	v_mbcnt_lo_u32_b32 v215, vcc_lo, 0
	v_mbcnt_hi_u32_b32 v216, vcc_hi, 0
	v_add_lshl_u32 v215, v215, s74, 3
	v_add_lshl_u32 v216, v216, s75, 3
	v_cndmask_b32_e64 v215, v216, v215, s[6:7]
	v_add_u32_e32 v215, v126, v215
	s_mov_b64 exec, vcc
	ds_write_b64 v215, v[226:227]
	s_mov_b64 exec, -1
	s_add_i32 s74, s74, s4
	s_add_i32 s75, s75, s5
	v_mfma_f32_32x32x16_bf16 v[148:163], v[64:67], v[184:187], v[148:163]
	v_max_i32_e32 v164, 0, v164
	v_max_i32_e32 v165, 0, v165
	v_fma_f32 v212, v104, v164, 0
	v_fma_f32 v214, v105, v165, 0
	v_max_i32_e32 v166, 0, v166
	v_max_i32_e32 v167, 0, v167
	v_fmac_f32_e32 v212, v106, v166
	v_fmac_f32_e32 v214, v107, v167
	v_max_i32_e32 v168, 0, v168
	v_max_i32_e32 v169, 0, v169
	v_fmac_f32_e32 v212, v108, v168
	v_fmac_f32_e32 v214, v109, v169
	v_max_i32_e32 v170, 0, v170
	v_max_i32_e32 v171, 0, v171
	v_fmac_f32_e32 v212, v110, v170
	v_fmac_f32_e32 v214, v111, v171
	v_mfma_f32_32x32x16_bf16 v[148:163], v[68:71], v[188:191], v[148:163]
	v_max_i32_e32 v172, 0, v172
	v_max_i32_e32 v173, 0, v173
	v_fmac_f32_e32 v212, v112, v172
	v_fmac_f32_e32 v214, v113, v173
	v_max_i32_e32 v174, 0, v174
	v_max_i32_e32 v175, 0, v175
	v_fmac_f32_e32 v212, v114, v174
	v_fmac_f32_e32 v214, v115, v175
	v_max_i32_e32 v176, 0, v176
	v_max_i32_e32 v177, 0, v177
	v_fmac_f32_e32 v212, v116, v176
	v_fmac_f32_e32 v214, v117, v177
	v_max_i32_e32 v178, 0, v178
	v_max_i32_e32 v179, 0, v179
	v_fmac_f32_e32 v212, v118, v178
	v_fmac_f32_e32 v214, v119, v179
	v_add_f32_e32 v212, v212, v214
	v_mfma_f32_32x32x16_bf16 v[148:163], v[72:75], v[192:195], v[148:163]
	v_cmp_gt_f32_e32 vcc, v212, v128
	v_or_b32_e32 v213, 96, v223
	s_bcnt1_i32_b32 s4, vcc_lo
	s_bcnt1_i32_b32 s5, vcc_hi
	v_mbcnt_lo_u32_b32 v215, vcc_lo, 0
	v_mbcnt_hi_u32_b32 v216, vcc_hi, 0
	v_add_lshl_u32 v215, v215, s74, 3
	v_add_lshl_u32 v216, v216, s75, 3
	v_cndmask_b32_e64 v215, v216, v215, s[6:7]
	v_add_u32_e32 v215, v126, v215
	s_mov_b64 exec, vcc
	ds_write_b64 v215, v[212:213]
	s_mov_b64 exec, -1
	s_add_i32 s74, s74, s4
	s_add_i32 s75, s75, s5
	s_add_i32 s95, s95, 1
	v_mov_b32_e32 v219, v220
	v_add_u32_e32 v223, 0x80, v223
	s_add_i32 s4, s95, 1
	s_cmp_lt_i32 s4, s93
	s_cbranch_scc1 .Lidx_tile

; __device__ __forceinline__ float bf_lo(unsigned v) { return __uint_as_float(v << 16); }
; __device__ __forceinline__ float bf_hi(unsigned v) { return __uint_as_float(v & 0xffff0000u); }
; __global__ void __launch_bounds__(512, 2) mega(Params p) {
;     ...
;             const int t = (int)(it >> 7), c = ((int)it & 127) * 8, g = c >> 8, w = 2 << g;
;             const int lo = (t + 1 - w) > 0 ? (t + 1 - w) : 0; const float inv = 1.f / (float)(t + 1 - lo);
;             float s[8] = {0.f, 0.f, 0.f, 0.f, 0.f, 0.f, 0.f, 0.f}; u32x4 v = {0u, 0u, 0u, 0u};
;             for (int tt = lo; tt <= t; ++tt) { v = *(const u32x4*)(Z + (size_t)tt * ZLD + c);
;                 s[0] += bf_lo(v.x); s[1] += bf_hi(v.x); s[2] += bf_lo(v.y); s[3] += bf_hi(v.y); s[4] += bf_lo(v.z); s[5] += bf_hi(v.z); s[6] += bf_lo(v.w); s[7] += bf_hi(v.w); }
.LBB0_1169:
	v_alignbit_b32 v20, v5, v4, 7
	v_bfe_u32 v17, v4, 5, 2
	v_lshlrev_b32_e64 v14, v17, -2
	v_add_u32_e32 v18, 1, v20
	v_add_u32_e32 v19, v14, v18
	v_mov_b32_e32 v13, 0
	v_cmp_le_i32_e32 vcc, v19, v20
	v_mov_b32_e32 v3, 0
	v_mov_b32_e32 v12, v13
	v_mov_b32_e32 v11, v13
	v_mov_b32_e32 v10, v13
	v_mov_b32_e32 v9, v13
	v_mov_b32_e32 v8, v13
	v_mov_b32_e32 v7, v13
	v_mov_b32_e32 v6, v13
	v_mov_b32_e32 v2, 0
	v_mov_b32_e32 v1, 0
	v_mov_b32_e32 v0, 0
	s_mov_b64 s[10:11], exec
	v_lshlrev_b32_e32 v212, 1, v16
	v_and_b32_e32 v90, 0x7f0, v212
	v_max_i32_e32 v212, 0, v19
	v_sub_u32_e32 v213, v18, v212
	v_mul_lo_u32 v214, v20, s81
	v_add_u32_e32 v214, v214, v90
	s_and_b32 s12, s33, 64
	s_cmp_lg_u32 s12, 0
	s_cbranch_scc1 .Lp2a_w16
	v_cmp_lt_i32_e32 vcc, 3, v213
	s_and_saveexec_b64 s[12:13], vcc
	v_add_u32_e32 v215, 0xffff8200, v214
	global_load_dwordx4 v[156:159], v215, s[42:43]
	s_mov_b64 exec, s[12:13]
	v_cmp_lt_i32_e32 vcc, 2, v213
	s_and_saveexec_b64 s[12:13], vcc
	v_add_u32_e32 v215, 0xffffac00, v214
	global_load_dwordx4 v[152:155], v215, s[42:43]
	s_mov_b64 exec, s[12:13]
	v_cmp_lt_i32_e32 vcc, 1, v213
	s_and_saveexec_b64 s[12:13], vcc
	v_add_u32_e32 v215, 0xffffd600, v214
	global_load_dwordx4 v[148:151], v215, s[42:43]
	s_mov_b64 exec, s[12:13]
	v_cmp_lt_i32_e32 vcc, 0, v213
	s_and_saveexec_b64 s[12:13], vcc
	global_load_dwordx4 v[0:3], v214, s[42:43]
	s_mov_b64 exec, s[12:13]
	s_waitcnt vmcnt(0)
	v_cmp_lt_i32_e32 vcc, 3, v213
	s_and_saveexec_b64 s[12:13], vcc
	v_and_b32_e32 v22, 0xffff0000, v156
	v_lshlrev_b32_e32 v23, 16, v156
	v_and_b32_e32 v24, 0xffff0000, v157
	v_lshlrev_b32_e32 v25, 16, v157
	v_and_b32_e32 v26, 0xffff0000, v158
	v_lshlrev_b32_e32 v27, 16, v158
	v_and_b32_e32 v28, 0xffff0000, v159
	v_lshlrev_b32_e32 v29, 16, v159
	v_pk_add_f32 v[12:13], v[12:13], v[22:23]
	v_pk_add_f32 v[10:11], v[10:11], v[24:25]
	v_pk_add_f32 v[8:9], v[8:9], v[26:27]
	v_pk_add_f32 v[6:7], v[6:7], v[28:29]
	s_mov_b64 exec, s[12:13]
	v_cmp_lt_i32_e32 vcc, 2, v213
	s_and_saveexec_b64 s[12:13], vcc
	v_and_b32_e32 v22, 0xffff0000, v152
	v_lshlrev_b32_e32 v23, 16, v152
	v_and_b32_e32 v24, 0xffff0000, v153
	v_lshlrev_b32_e32 v25, 16, v153
	v_and_b32_e32 v26, 0xffff0000, v154
	v_lshlrev_b32_e32 v27, 16, v154
	v_and_b32_e32 v28, 0xffff0000, v155
	v_lshlrev_b32_e32 v29, 16, v155
	v_pk_add_f32 v[12:13], v[12:13], v[22:23]
	v_pk_add_f32 v[10:11], v[10:11], v[24:25]
	v_pk_add_f32 v[8:9], v[8:9], v[26:27]
	v_pk_add_f32 v[6:7], v[6:7], v[28:29]
	s_mov_b64 exec, s[12:13]
	v_cmp_lt_i32_e32 vcc, 1, v213
	s_and_saveexec_b64 s[12:13], vcc
	v_and_b32_e32 v22, 0xffff0000, v148
	v_lshlrev_b32_e32 v23, 16, v148
	v_and_b32_e32 v24, 0xffff0000, v149
	v_lshlrev_b32_e32 v25, 16, v149
	v_and_b32_e32 v26, 0xffff0000, v150
	v_lshlrev_b32_e32 v27, 16, v150
	v_and_b32_e32 v28, 0xffff0000, v151
	v_lshlrev_b32_e32 v29, 16, v151
	v_pk_add_f32 v[12:13], v[12:13], v[22:23]
	v_pk_add_f32 v[10:11], v[10:11], v[24:25]
	v_pk_add_f32 v[8:9], v[8:9], v[26:27]
	v_pk_add_f32 v[6:7], v[6:7], v[28:29]
	s_mov_b64 exec, s[12:13]
	v_cmp_lt_i32_e32 vcc, 0, v213
	s_and_saveexec_b64 s[12:13], vcc
	v_and_b32_e32 v22, 0xffff0000, v0
	v_lshlrev_b32_e32 v23, 16, v0
	v_and_b32_e32 v24, 0xffff0000, v1
	v_lshlrev_b32_e32 v25, 16, v1
	v_and_b32_e32 v26, 0xffff0000, v2
	v_lshlrev_b32_e32 v27, 16, v2
	v_and_b32_e32 v28, 0xffff0000, v3
	v_lshlrev_b32_e32 v29, 16, v3
	v_pk_add_f32 v[12:13], v[12:13], v[22:23]
	v_pk_add_f32 v[10:11], v[10:11], v[24:25]
	v_pk_add_f32 v[8:9], v[8:9], v[26:27]
	v_pk_add_f32 v[6:7], v[6:7], v[28:29]
	s_mov_b64 exec, s[12:13]
	s_branch .LBB0_1168
.Lp2a_w16:
	v_cmp_lt_i32_e32 vcc, 15, v213
	s_and_saveexec_b64 s[12:13], vcc
	v_add_u32_e32 v215, 0xfffd8a00, v214
	global_load_dwordx4 v[204:207], v215, s[42:43]
	s_mov_b64 exec, s[12:13]
	v_cmp_lt_i32_e32 vcc, 14, v213
	s_and_saveexec_b64 s[12:13], vcc
	v_add_u32_e32 v215, 0xfffdb400, v214
	global_load_dwordx4 v[200:203], v215, s[42:43]
	s_mov_b64 exec, s[12:13]
	v_cmp_lt_i32_e32 vcc, 13, v213
	s_and_saveexec_b64 s[12:13], vcc
	v_add_u32_e32 v215, 0xfffdde00, v214
	global_load_dwordx4 v[196:199], v215, s[42:43]
	s_mov_b64 exec, s[12:13]
	v_cmp_lt_i32_e32 vcc, 12, v213
	s_and_saveexec_b64 s[12:13], vcc
	v_add_u32_e32 v215, 0xfffe0800, v214
	global_load_dwordx4 v[192:195], v215, s[42:43]
	s_mov_b64 exec, s[12:13]
	v_cmp_lt_i32_e32 vcc, 11, v213
	s_and_saveexec_b64 s[12:13], vcc
	v_add_u32_e32 v215, 0xfffe3200, v214
	global_load_dwordx4 v[188:191], v215, s[42:43]
	s_mov_b64 exec, s[12:13]
	v_cmp_lt_i32_e32 vcc, 10, v213
	s_and_saveexec_b64 s[12:13], vcc
	v_add_u32_e32 v215, 0xfffe5c00, v214
	global_load_dwordx4 v[184:187], v215, s[42:43]
	s_mov_b64 exec, s[12:13]
	v_cmp_lt_i32_e32 vcc, 9, v213
	s_and_saveexec_b64 s[12:13], vcc
	v_add_u32_e32 v215, 0xfffe8600, v214
	global_load_dwordx4 v[180:183], v215, s[42:43]
	s_mov_b64 exec, s[12:13]
	v_cmp_lt_i32_e32 vcc, 8, v213
	s_and_saveexec_b64 s[12:13], vcc
	v_add_u32_e32 v215, 0xfffeb000, v214
	global_load_dwordx4 v[176:179], v215, s[42:43]
	s_mov_b64 exec, s[12:13]
	v_cmp_lt_i32_e32 vcc, 7, v213
	s_and_saveexec_b64 s[12:13], vcc
	v_add_u32_e32 v215, 0xfffeda00, v214
	global_load_dwordx4 v[172:175], v215, s[42:43]
	s_mov_b64 exec, s[12:13]
	v_cmp_lt_i32_e32 vcc, 6, v213
	s_and_saveexec_b64 s[12:13], vcc
	v_add_u32_e32 v215, 0xffff0400, v214
	global_load_dwordx4 v[168:171], v215, s[42:43]
	s_mov_b64 exec, s[12:13]
	v_cmp_lt_i32_e32 vcc, 5, v213
	s_and_saveexec_b64 s[12:13], vcc
	v_add_u32_e32 v215, 0xffff2e00, v214
	global_load_dwordx4 v[164:167], v215, s[42:43]
	s_mov_b64 exec, s[12:13]
	v_cmp_lt_i32_e32 vcc, 4, v213
	s_and_saveexec_b64 s[12:13], vcc
	v_add_u32_e32 v215, 0xffff5800, v214
	global_load_dwordx4 v[160:163], v215, s[42:43]
	s_mov_b64 exec, s[12:13]
	v_cmp_lt_i32_e32 vcc, 3, v213
	s_and_saveexec_b64 s[12:13], vcc
	v_add_u32_e32 v215, 0xffff8200, v214
	global_load_dwordx4 v[156:159], v215, s[42:43]
	s_mov_b64 exec, s[12:13]
	v_cmp_lt_i32_e32 vcc, 2, v213
	s_and_saveexec_b64 s[12:13], vcc
	v_add_u32_e32 v215, 0xffffac00, v214
	global_load_dwordx4 v[152:155], v215, s[42:43]
	s_mov_b64 exec, s[12:13]
	v_cmp_lt_i32_e32 vcc, 1, v213
	s_and_saveexec_b64 s[12:13], vcc
	v_add_u32_e32 v215, 0xffffd600, v214
	global_load_dwordx4 v[148:151], v215, s[42:43]
	s_mov_b64 exec, s[12:13]
	v_cmp_lt_i32_e32 vcc, 0, v213
	s_and_saveexec_b64 s[12:13], vcc
	global_load_dwordx4 v[0:3], v214, s[42:43]
	s_mov_b64 exec, s[12:13]
	s_waitcnt vmcnt(0)
; __device__ __forceinline__ float bf_lo(unsigned v) { return __uint_as_float(v << 16); }
; __device__ __forceinline__ float bf_hi(unsigned v) { return __uint_as_float(v & 0xffff0000u); }
; __global__ void __launch_bounds__(512, 2) mega(Params p) {
;     ...
;             for (int tt = lo; tt <= t; ++tt) { v = *(const u32x4*)(Z + (size_t)tt * ZLD + c);
;                 s[0] += bf_lo(v.x); s[1] += bf_hi(v.x); s[2] += bf_lo(v.y); s[3] += bf_hi(v.y); s[4] += bf_lo(v.z); s[5] += bf_hi(v.z); s[6] += bf_lo(v.w); s[7] += bf_hi(v.w); }
	v_cmp_lt_i32_e32 vcc, 15, v213
	s_and_saveexec_b64 s[12:13], vcc
	v_and_b32_e32 v22, 0xffff0000, v204
	v_lshlrev_b32_e32 v23, 16, v204
	v_and_b32_e32 v24, 0xffff0000, v205
	v_lshlrev_b32_e32 v25, 16, v205
	v_and_b32_e32 v26, 0xffff0000, v206
	v_lshlrev_b32_e32 v27, 16, v206
	v_and_b32_e32 v28, 0xffff0000, v207
	v_lshlrev_b32_e32 v29, 16, v207
	v_pk_add_f32 v[12:13], v[12:13], v[22:23]
	v_pk_add_f32 v[10:11], v[10:11], v[24:25]
	v_pk_add_f32 v[8:9], v[8:9], v[26:27]
	v_pk_add_f32 v[6:7], v[6:7], v[28:29]
	s_mov_b64 exec, s[12:13]
	v_cmp_lt_i32_e32 vcc, 14, v213
	s_and_saveexec_b64 s[12:13], vcc
	v_and_b32_e32 v22, 0xffff0000, v200
	v_lshlrev_b32_e32 v23, 16, v200
	v_and_b32_e32 v24, 0xffff0000, v201
	v_lshlrev_b32_e32 v25, 16, v201
	v_and_b32_e32 v26, 0xffff0000, v202
	v_lshlrev_b32_e32 v27, 16, v202
	v_and_b32_e32 v28, 0xffff0000, v203
	v_lshlrev_b32_e32 v29, 16, v203
	v_pk_add_f32 v[12:13], v[12:13], v[22:23]
	v_pk_add_f32 v[10:11], v[10:11], v[24:25]
	v_pk_add_f32 v[8:9], v[8:9], v[26:27]
	v_pk_add_f32 v[6:7], v[6:7], v[28:29]
	s_mov_b64 exec, s[12:13]
	v_cmp_lt_i32_e32 vcc, 13, v213
	s_and_saveexec_b64 s[12:13], vcc
	v_and_b32_e32 v22, 0xffff0000, v196
	v_lshlrev_b32_e32 v23, 16, v196
	v_and_b32_e32 v24, 0xffff0000, v197
	v_lshlrev_b32_e32 v25, 16, v197
	v_and_b32_e32 v26, 0xffff0000, v198
	v_lshlrev_b32_e32 v27, 16, v198
	v_and_b32_e32 v28, 0xffff0000, v199
	v_lshlrev_b32_e32 v29, 16, v199
	v_pk_add_f32 v[12:13], v[12:13], v[22:23]
	v_pk_add_f32 v[10:11], v[10:11], v[24:25]
	v_pk_add_f32 v[8:9], v[8:9], v[26:27]
	v_pk_add_f32 v[6:7], v[6:7], v[28:29]
	s_mov_b64 exec, s[12:13]
	v_cmp_lt_i32_e32 vcc, 12, v213
	s_and_saveexec_b64 s[12:13], vcc
	v_and_b32_e32 v22, 0xffff0000, v192
	v_lshlrev_b32_e32 v23, 16, v192
	v_and_b32_e32 v24, 0xffff0000, v193
	v_lshlrev_b32_e32 v25, 16, v193
	v_and_b32_e32 v26, 0xffff0000, v194
	v_lshlrev_b32_e32 v27, 16, v194
	v_and_b32_e32 v28, 0xffff0000, v195
	v_lshlrev_b32_e32 v29, 16, v195
	v_pk_add_f32 v[12:13], v[12:13], v[22:23]
	v_pk_add_f32 v[10:11], v[10:11], v[24:25]
	v_pk_add_f32 v[8:9], v[8:9], v[26:27]
	v_pk_add_f32 v[6:7], v[6:7], v[28:29]
	s_mov_b64 exec, s[12:13]
	v_cmp_lt_i32_e32 vcc, 11, v213
	s_and_saveexec_b64 s[12:13], vcc
	v_and_b32_e32 v22, 0xffff0000, v188
	v_lshlrev_b32_e32 v23, 16, v188
	v_and_b32_e32 v24, 0xffff0000, v189
	v_lshlrev_b32_e32 v25, 16, v189
	v_and_b32_e32 v26, 0xffff0000, v190
	v_lshlrev_b32_e32 v27, 16, v190
	v_and_b32_e32 v28, 0xffff0000, v191
	v_lshlrev_b32_e32 v29, 16, v191
	v_pk_add_f32 v[12:13], v[12:13], v[22:23]
	v_pk_add_f32 v[10:11], v[10:11], v[24:25]
	v_pk_add_f32 v[8:9], v[8:9], v[26:27]
	v_pk_add_f32 v[6:7], v[6:7], v[28:29]
	s_mov_b64 exec, s[12:13]
	v_cmp_lt_i32_e32 vcc, 10, v213
	s_and_saveexec_b64 s[12:13], vcc
	v_and_b32_e32 v22, 0xffff0000, v184
	v_lshlrev_b32_e32 v23, 16, v184
	v_and_b32_e32 v24, 0xffff0000, v185
	v_lshlrev_b32_e32 v25, 16, v185
	v_and_b32_e32 v26, 0xffff0000, v186
	v_lshlrev_b32_e32 v27, 16, v186
	v_and_b32_e32 v28, 0xffff0000, v187
	v_lshlrev_b32_e32 v29, 16, v187
	v_pk_add_f32 v[12:13], v[12:13], v[22:23]
	v_pk_add_f32 v[10:11], v[10:11], v[24:25]
	v_pk_add_f32 v[8:9], v[8:9], v[26:27]
	v_pk_add_f32 v[6:7], v[6:7], v[28:29]
	s_mov_b64 exec, s[12:13]
	v_cmp_lt_i32_e32 vcc, 9, v213
	s_and_saveexec_b64 s[12:13], vcc
	v_and_b32_e32 v22, 0xffff0000, v180
	v_lshlrev_b32_e32 v23, 16, v180
	v_and_b32_e32 v24, 0xffff0000, v181
	v_lshlrev_b32_e32 v25, 16, v181
	v_and_b32_e32 v26, 0xffff0000, v182
	v_lshlrev_b32_e32 v27, 16, v182
	v_and_b32_e32 v28, 0xffff0000, v183
	v_lshlrev_b32_e32 v29, 16, v183
	v_pk_add_f32 v[12:13], v[12:13], v[22:23]
	v_pk_add_f32 v[10:11], v[10:11], v[24:25]
	v_pk_add_f32 v[8:9], v[8:9], v[26:27]
	v_pk_add_f32 v[6:7], v[6:7], v[28:29]
	s_mov_b64 exec, s[12:13]
	v_cmp_lt_i32_e32 vcc, 8, v213
	s_and_saveexec_b64 s[12:13], vcc
	v_and_b32_e32 v22, 0xffff0000, v176
	v_lshlrev_b32_e32 v23, 16, v176
	v_and_b32_e32 v24, 0xffff0000, v177
	v_lshlrev_b32_e32 v25, 16, v177
	v_and_b32_e32 v26, 0xffff0000, v178
	v_lshlrev_b32_e32 v27, 16, v178
	v_and_b32_e32 v28, 0xffff0000, v179
	v_lshlrev_b32_e32 v29, 16, v179
	v_pk_add_f32 v[12:13], v[12:13], v[22:23]
	v_pk_add_f32 v[10:11], v[10:11], v[24:25]
	v_pk_add_f32 v[8:9], v[8:9], v[26:27]
	v_pk_add_f32 v[6:7], v[6:7], v[28:29]
	s_mov_b64 exec, s[12:13]
; __device__ __forceinline__ unsigned cvt_pk_bf16(float lo, float hi) { unsigned r; asm volatile("v_cvt_pk_bf16_f32 %0, %1, %2" : "=v"(r) : "v"(lo), "v"(hi)); return r; }
; __device__ __forceinline__ float bf_lo(unsigned v) { return __uint_as_float(v << 16); }
; __device__ __forceinline__ float bf_hi(unsigned v) { return __uint_as_float(v & 0xffff0000u); }
; __global__ void __launch_bounds__(512, 2) mega(Params p) {
;     ...
;             for (int tt = lo; tt <= t; ++tt) { v = *(const u32x4*)(Z + (size_t)tt * ZLD + c);
;                 s[0] += bf_lo(v.x); s[1] += bf_hi(v.x); s[2] += bf_lo(v.y); s[3] += bf_hi(v.y); s[4] += bf_lo(v.z); s[5] += bf_hi(v.z); s[6] += bf_lo(v.w); s[7] += bf_hi(v.w); }
;             u32x4 o; o.x = cvt_pk_bf16(s[0] * inv - bf_lo(v.x), s[1] * inv - bf_hi(v.x)); o.y = cvt_pk_bf16(s[2] * inv - bf_lo(v.y), s[3] * inv - bf_hi(v.y));
;             o.z = cvt_pk_bf16(s[4] * inv - bf_lo(v.z), s[5] * inv - bf_hi(v.z)); o.w = cvt_pk_bf16(s[6] * inv - bf_lo(v.w), s[7] * inv - bf_hi(v.w));
;             *(u32x4*)(Dp + ((size_t)g * S_ + t) * 256 + (c & 255)) = o;
;         }
	v_cmp_lt_i32_e32 vcc, 7, v213
	s_and_saveexec_b64 s[12:13], vcc
	v_and_b32_e32 v22, 0xffff0000, v172
	v_lshlrev_b32_e32 v23, 16, v172
	v_and_b32_e32 v24, 0xffff0000, v173
	v_lshlrev_b32_e32 v25, 16, v173
	v_and_b32_e32 v26, 0xffff0000, v174
	v_lshlrev_b32_e32 v27, 16, v174
	v_and_b32_e32 v28, 0xffff0000, v175
	v_lshlrev_b32_e32 v29, 16, v175
	v_pk_add_f32 v[12:13], v[12:13], v[22:23]
	v_pk_add_f32 v[10:11], v[10:11], v[24:25]
	v_pk_add_f32 v[8:9], v[8:9], v[26:27]
	v_pk_add_f32 v[6:7], v[6:7], v[28:29]
	s_mov_b64 exec, s[12:13]
	v_cmp_lt_i32_e32 vcc, 6, v213
	s_and_saveexec_b64 s[12:13], vcc
	v_and_b32_e32 v22, 0xffff0000, v168
	v_lshlrev_b32_e32 v23, 16, v168
	v_and_b32_e32 v24, 0xffff0000, v169
	v_lshlrev_b32_e32 v25, 16, v169
	v_and_b32_e32 v26, 0xffff0000, v170
	v_lshlrev_b32_e32 v27, 16, v170
	v_and_b32_e32 v28, 0xffff0000, v171
	v_lshlrev_b32_e32 v29, 16, v171
	v_pk_add_f32 v[12:13], v[12:13], v[22:23]
	v_pk_add_f32 v[10:11], v[10:11], v[24:25]
	v_pk_add_f32 v[8:9], v[8:9], v[26:27]
	v_pk_add_f32 v[6:7], v[6:7], v[28:29]
	s_mov_b64 exec, s[12:13]
	v_cmp_lt_i32_e32 vcc, 5, v213
	s_and_saveexec_b64 s[12:13], vcc
	v_and_b32_e32 v22, 0xffff0000, v164
	v_lshlrev_b32_e32 v23, 16, v164
	v_and_b32_e32 v24, 0xffff0000, v165
	v_lshlrev_b32_e32 v25, 16, v165
	v_and_b32_e32 v26, 0xffff0000, v166
	v_lshlrev_b32_e32 v27, 16, v166
	v_and_b32_e32 v28, 0xffff0000, v167
	v_lshlrev_b32_e32 v29, 16, v167
	v_pk_add_f32 v[12:13], v[12:13], v[22:23]
	v_pk_add_f32 v[10:11], v[10:11], v[24:25]
	v_pk_add_f32 v[8:9], v[8:9], v[26:27]
	v_pk_add_f32 v[6:7], v[6:7], v[28:29]
	s_mov_b64 exec, s[12:13]
	v_cmp_lt_i32_e32 vcc, 4, v213
	s_and_saveexec_b64 s[12:13], vcc
	v_and_b32_e32 v22, 0xffff0000, v160
	v_lshlrev_b32_e32 v23, 16, v160
	v_and_b32_e32 v24, 0xffff0000, v161
	v_lshlrev_b32_e32 v25, 16, v161
	v_and_b32_e32 v26, 0xffff0000, v162
	v_lshlrev_b32_e32 v27, 16, v162
	v_and_b32_e32 v28, 0xffff0000, v163
	v_lshlrev_b32_e32 v29, 16, v163
	v_pk_add_f32 v[12:13], v[12:13], v[22:23]
	v_pk_add_f32 v[10:11], v[10:11], v[24:25]
	v_pk_add_f32 v[8:9], v[8:9], v[26:27]
	v_pk_add_f32 v[6:7], v[6:7], v[28:29]
	s_mov_b64 exec, s[12:13]
	v_cmp_lt_i32_e32 vcc, 3, v213
	s_and_saveexec_b64 s[12:13], vcc
	v_and_b32_e32 v22, 0xffff0000, v156
	v_lshlrev_b32_e32 v23, 16, v156
	v_and_b32_e32 v24, 0xffff0000, v157
	v_lshlrev_b32_e32 v25, 16, v157
	v_and_b32_e32 v26, 0xffff0000, v158
	v_lshlrev_b32_e32 v27, 16, v158
	v_and_b32_e32 v28, 0xffff0000, v159
	v_lshlrev_b32_e32 v29, 16, v159
	v_pk_add_f32 v[12:13], v[12:13], v[22:23]
	v_pk_add_f32 v[10:11], v[10:11], v[24:25]
	v_pk_add_f32 v[8:9], v[8:9], v[26:27]
	v_pk_add_f32 v[6:7], v[6:7], v[28:29]
	s_mov_b64 exec, s[12:13]
	v_cmp_lt_i32_e32 vcc, 2, v213
	s_and_saveexec_b64 s[12:13], vcc
	v_and_b32_e32 v22, 0xffff0000, v152
	v_lshlrev_b32_e32 v23, 16, v152
	v_and_b32_e32 v24, 0xffff0000, v153
	v_lshlrev_b32_e32 v25, 16, v153
	v_and_b32_e32 v26, 0xffff0000, v154
	v_lshlrev_b32_e32 v27, 16, v154
	v_and_b32_e32 v28, 0xffff0000, v155
	v_lshlrev_b32_e32 v29, 16, v155
	v_pk_add_f32 v[12:13], v[12:13], v[22:23]
	v_pk_add_f32 v[10:11], v[10:11], v[24:25]
	v_pk_add_f32 v[8:9], v[8:9], v[26:27]
	v_pk_add_f32 v[6:7], v[6:7], v[28:29]
	s_mov_b64 exec, s[12:13]
	v_cmp_lt_i32_e32 vcc, 1, v213
	s_and_saveexec_b64 s[12:13], vcc
	v_and_b32_e32 v22, 0xffff0000, v148
	v_lshlrev_b32_e32 v23, 16, v148
	v_and_b32_e32 v24, 0xffff0000, v149
	v_lshlrev_b32_e32 v25, 16, v149
	v_and_b32_e32 v26, 0xffff0000, v150
	v_lshlrev_b32_e32 v27, 16, v150
	v_and_b32_e32 v28, 0xffff0000, v151
	v_lshlrev_b32_e32 v29, 16, v151
	v_pk_add_f32 v[12:13], v[12:13], v[22:23]
	v_pk_add_f32 v[10:11], v[10:11], v[24:25]
	v_pk_add_f32 v[8:9], v[8:9], v[26:27]
	v_pk_add_f32 v[6:7], v[6:7], v[28:29]
	s_mov_b64 exec, s[12:13]
	v_cmp_lt_i32_e32 vcc, 0, v213
	s_and_saveexec_b64 s[12:13], vcc
	v_and_b32_e32 v22, 0xffff0000, v0
	v_lshlrev_b32_e32 v23, 16, v0
	v_and_b32_e32 v24, 0xffff0000, v1
	v_lshlrev_b32_e32 v25, 16, v1
	v_and_b32_e32 v26, 0xffff0000, v2
	v_lshlrev_b32_e32 v27, 16, v2
	v_and_b32_e32 v28, 0xffff0000, v3
	v_lshlrev_b32_e32 v29, 16, v3
	v_pk_add_f32 v[12:13], v[12:13], v[22:23]
	v_pk_add_f32 v[10:11], v[10:11], v[24:25]
	v_pk_add_f32 v[8:9], v[8:9], v[26:27]
	v_pk_add_f32 v[6:7], v[6:7], v[28:29]
	s_mov_b64 exec, s[12:13]
	s_branch .LBB0_1168

; __device__ __forceinline__ unsigned cvt_pk_bf16(float lo, float hi) { unsigned r; asm volatile("v_cvt_pk_bf16_f32 %0, %1, %2" : "=v"(r) : "v"(lo), "v"(hi)); return r; }
; __device__ __forceinline__ float bf_lo(unsigned v) { return __uint_as_float(v << 16); }
; __device__ __forceinline__ float bf_hi(unsigned v) { return __uint_as_float(v & 0xffff0000u); }
; __global__ void __launch_bounds__(512, 2) mega(Params p) {
;     ...
;             for (int t = gw; t < S_; t += ngw) {
; #pragma unroll
;                 for (int which = 0; which < 2; ++which) {
;                     u32x4* ptr = (u32x4*)(Z + (size_t)t * ZLD + (which ? OFF_K : OFF_Q) + lane * 16);
;                     const u32x4 a = ptr[0], b = ptr[1];
;                     float f[16] = {bf_lo(a.x), bf_hi(a.x), bf_lo(a.y), bf_hi(a.y), bf_lo(a.z), bf_hi(a.z), bf_lo(a.w), bf_hi(a.w), bf_lo(b.x), bf_hi(b.x), bf_lo(b.y), bf_hi(b.y), bf_lo(b.z), bf_hi(b.z), bf_lo(b.w), bf_hi(b.w)};
;                     float ss = 0.f;
; #pragma unroll
;                     for (int e = 0; e < 16; ++e) ss = fmaf(f[e], f[e], ss);
;                     ss += __shfl_xor(ss, 1); ss += __shfl_xor(ss, 2); ss += __shfl_xor(ss, 4);
;                     const float rinv = 1.f / sqrtf(ss * (1.f / 128.f) + EPS_);
; #pragma unroll
;                     for (int e = 0; e < 16; ++e) f[e] = f[e] * rinv * (which ? 1.f : gq[e]);
;                     if (which == 0) {
;                         u32x4 oa, ob; oa.x = cvt_pk_bf16(f[0], f[1]); oa.y = cvt_pk_bf16(f[2], f[3]); oa.z = cvt_pk_bf16(f[4], f[5]); oa.w = cvt_pk_bf16(f[6], f[7]);
;                         ob.x = cvt_pk_bf16(f[8], f[9]); ob.y = cvt_pk_bf16(f[10], f[11]); ob.z = cvt_pk_bf16(f[12], f[13]); ob.w = cvt_pk_bf16(f[14], f[15]);
;                         ptr[0] = oa; ptr[1] = ob;
.LBB0_1175:
	v_lshl_add_u64 v[8:9], s[60:61], 0, v[4:5]
	s_mov_b64 s[6:7], 0xa000800
	v_add_co_u32_e32 v48, vcc, 0xa000000, v8
	v_lshl_add_u64 v[36:37], v[8:9], 0, s[6:7]
	s_nop 0
	v_addc_co_u32_e32 v49, vcc, 0, v9, vcc
	global_load_dwordx4 v[32:35], v[48:49], off offset:2048
	s_nop 0
	global_load_dwordx4 v[36:39], v[36:37], off offset:16
	s_mov_b64 s[12:13], 0xa001000
	v_lshl_add_u64 v[164:165], v[8:9], 0, s[12:13]
	global_load_dwordx4 v[148:151], v[164:165], off
	global_load_dwordx4 v[152:155], v[164:165], off offset:16
	global_load_dwordx4 v[156:159], v[164:165], off offset:2048
	global_load_dwordx4 v[160:163], v[164:165], off offset:2064
	s_mov_b32 s4, 0xa001000
	v_add_co_u32_e64 v50, s[6:7], s4, v8
	s_mov_b64 s[8:9], 0xa001000
	s_nop 0
	v_addc_co_u32_e64 v51, s[6:7], 0, v9, s[6:7]
	v_lshl_add_u64 v[44:45], v[8:9], 0, s[8:9]
	v_lshl_add_u64 v[10:11], s[60:61], 0, v[6:7]
	v_mov_b32_e32 v0, 0
	v_mov_b32_e32 v1, 0
	v_mov_b32_e32 v2, 0
	v_mov_b32_e32 v3, 0
	s_add_i32 s10, s10, s82
	v_lshl_add_u64 v[6:7], v[6:7], 0, s[50:51]
	v_lshl_add_u64 v[4:5], v[4:5], 0, s[52:53]
	s_cmpk_gt_i32 s10, 0x3fff
	s_waitcnt vmcnt(5)
	v_lshlrev_b32_e32 v31, 16, v32
	v_and_b32_e32 v32, 0xffff0000, v32
	v_fma_f32 v53, v31, v31, 0
	v_lshlrev_b32_e32 v40, 16, v33
	v_fmac_f32_e32 v53, v32, v32
	v_and_b32_e32 v33, 0xffff0000, v33
	v_fmac_f32_e32 v53, v40, v40
	v_lshlrev_b32_e32 v41, 16, v34
	v_fmac_f32_e32 v53, v33, v33
	v_and_b32_e32 v34, 0xffff0000, v34
	v_fmac_f32_e32 v53, v41, v41
	v_lshlrev_b32_e32 v42, 16, v35
	v_fmac_f32_e32 v53, v34, v34
	v_and_b32_e32 v35, 0xffff0000, v35
	v_fmac_f32_e32 v53, v42, v42
	s_waitcnt vmcnt(4)
	v_lshlrev_b32_e32 v43, 16, v36
	v_fmac_f32_e32 v53, v35, v35
	v_and_b32_e32 v36, 0xffff0000, v36
	v_fmac_f32_e32 v53, v43, v43
	v_lshlrev_b32_e32 v46, 16, v37
	v_fmac_f32_e32 v53, v36, v36
	v_and_b32_e32 v37, 0xffff0000, v37
	v_fmac_f32_e32 v53, v46, v46
	v_lshlrev_b32_e32 v47, 16, v38
	v_fmac_f32_e32 v53, v37, v37
	v_and_b32_e32 v38, 0xffff0000, v38
	v_fmac_f32_e32 v53, v47, v47
	v_lshlrev_b32_e32 v52, 16, v39
	v_fmac_f32_e32 v53, v38, v38
	v_and_b32_e32 v39, 0xffff0000, v39
	v_fmac_f32_e32 v53, v52, v52
	v_fmac_f32_e32 v53, v39, v39
	ds_bpermute_b32 v54, v12, v53
	s_waitcnt lgkmcnt(0)
	v_add_f32_e32 v53, v53, v54
	ds_bpermute_b32 v54, v13, v53
	s_waitcnt lgkmcnt(0)
	v_add_f32_e32 v53, v53, v54
	ds_bpermute_b32 v54, v14, v53
	s_waitcnt lgkmcnt(0)
	v_add_f32_e32 v53, v53, v54
	v_fmamk_f32 v53, v53, 0x3c000000, v121
	v_mul_f32_e32 v54, 0x4f800000, v53
	v_cmp_gt_f32_e32 vcc, s39, v53
	s_nop 1
	v_cndmask_b32_e32 v53, v53, v54, vcc
	v_sqrt_f32_e32 v54, v53
	s_nop 0
	v_add_u32_e32 v55, -1, v54
	v_add_u32_e32 v56, 1, v54
	v_fma_f32 v57, -v55, v54, v53
	v_fma_f32 v58, -v56, v54, v53
	v_cmp_ge_f32_e64 s[6:7], 0, v57
	s_nop 1
	v_cndmask_b32_e64 v54, v54, v55, s[6:7]
	v_cmp_lt_f32_e64 s[6:7], 0, v58
	s_nop 1
	v_cndmask_b32_e64 v54, v54, v56, s[6:7]
	v_mul_f32_e32 v55, 0x37800000, v54
	v_cndmask_b32_e32 v54, v54, v55, vcc
	v_cmp_class_f32_e32 vcc, v53, v122
	s_mov_b32 s6, 0x1b800000
	s_nop 0
	v_cndmask_b32_e32 v53, v54, v53, vcc
	v_div_scale_f32 v54, s[4:5], v53, v53, 1.0
	v_rcp_f32_e32 v56, v54
	v_div_scale_f32 v55, vcc, 1.0, v53, 1.0
	s_mov_b64 s[4:5], 0xa001800
	v_fma_f32 v57, -v54, v56, 1.0
	v_fmac_f32_e32 v56, v57, v56
	v_mul_f32_e32 v57, v55, v56
	v_fma_f32 v58, -v54, v57, v55
	v_fmac_f32_e32 v57, v58, v56
	v_fma_f32 v54, -v54, v57, v55
	v_div_fmas_f32 v54, v54, v56, v57
	v_div_fixup_f32 v53, v54, v53, 1.0
	v_mul_f32_e32 v39, v53, v39
	v_mul_f32_e32 v38, v53, v38
	v_mul_f32_e32 v47, v53, v47
	v_mul_f32_e32 v37, v53, v37
	v_mul_f32_e32 v46, v53, v46
	v_mul_f32_e32 v36, v53, v36
	v_mul_f32_e32 v43, v53, v43
	v_mul_f32_e32 v35, v53, v35
	v_mul_f32_e32 v42, v53, v42
	v_mul_f32_e32 v34, v53, v34
	v_mul_f32_e32 v41, v53, v41
	v_mul_f32_e32 v33, v53, v33
	v_mul_f32_e32 v40, v53, v40
	v_mul_f32_e32 v32, v53, v32
	v_mul_f32_e32 v52, v53, v52
	v_mul_f32_e32 v31, v53, v31
	v_mul_f32_e32 v39, v39, v30
	v_mul_f32_e32 v38, v38, v28
	v_mul_f32_e32 v47, v47, v27
	v_mul_f32_e32 v37, v37, v26
	v_mul_f32_e32 v46, v46, v25
	v_mul_f32_e32 v36, v36, v24
	v_mul_f32_e32 v43, v43, v23
	v_mul_f32_e32 v35, v35, v22
	v_mul_f32_e32 v42, v42, v21
	v_mul_f32_e32 v34, v34, v20
	v_mul_f32_e32 v41, v41, v19
	v_mul_f32_e32 v33, v33, v18
	v_mul_f32_e32 v40, v40, v17
	v_mul_f32_e32 v32, v32, v16
	v_mul_f32_e32 v52, v52, v29
	v_mul_f32_e32 v31, v31, v15
	v_cvt_pk_bf16_f32 v32, v31, v32
	v_cvt_pk_bf16_f32 v33, v40, v33
	v_cvt_pk_bf16_f32 v34, v41, v34
	v_cvt_pk_bf16_f32 v35, v42, v35
	v_cvt_pk_bf16_f32 v36, v43, v36
	v_cvt_pk_bf16_f32 v37, v46, v37
	v_cvt_pk_bf16_f32 v38, v47, v38
	v_cvt_pk_bf16_f32 v39, v52, v39
	s_waitcnt vmcnt(2)
; __device__ __forceinline__ float bf_lo(unsigned v) { return __uint_as_float(v << 16); }
; __global__ void __launch_bounds__(512, 2) mega(Params p) {
;     ...
;                 for (int which = 0; which < 2; ++which) {
;                     u32x4* ptr = (u32x4*)(Z + (size_t)t * ZLD + (which ? OFF_K : OFF_Q) + lane * 16);
;                     const u32x4 a = ptr[0], b = ptr[1];
;                     float f[16] = {bf_lo(a.x), bf_hi(a.x), bf_lo(a.y), bf_hi(a.y), bf_lo(a.z), bf_hi(a.z), bf_lo(a.w), bf_hi(a.w), bf_lo(b.x), bf_hi(b.x), bf_lo(b.y), bf_hi(b.y), bf_lo(b.z), bf_hi(b.z), bf_lo(b.w), bf_hi(b.w)};
;                     float ss = 0.f;
; #pragma unroll
;                     for (int e = 0; e < 16; ++e) ss = fmaf(f[e], f[e], ss);
;                     ss += __shfl_xor(ss, 1); ss += __shfl_xor(ss, 2); ss += __shfl_xor(ss, 4);
;                     const float rinv = 1.f / sqrtf(ss * (1.f / 128.f) + EPS_);
; #pragma unroll
;                     for (int e = 0; e < 16; ++e) f[e] = f[e] * rinv * (which ? 1.f : gq[e]);
;                     if (which == 0) {
;                         u32x4 oa, ob; oa.x = cvt_pk_bf16(f[0], f[1]); oa.y = cvt_pk_bf16(f[2], f[3]); oa.z = cvt_pk_bf16(f[4], f[5]); oa.w = cvt_pk_bf16(f[6], f[7]);
;                         ob.x = cvt_pk_bf16(f[8], f[9]); ob.y = cvt_pk_bf16(f[10], f[11]); ob.z = cvt_pk_bf16(f[12], f[13]); ob.w = cvt_pk_bf16(f[14], f[15]);
;                         ptr[0] = oa; ptr[1] = ob;
;                     } else {
;                         int w0 = 0, w1 = 0, w2 = 0, w3 = 0;
;                         w0 = __builtin_amdgcn_cvt_pk_fp8_f32(f[0], f[1], w0, false); w0 = __builtin_amdgcn_cvt_pk_fp8_f32(f[2], f[3], w0, true);
;                         w1 = __builtin_amdgcn_cvt_pk_fp8_f32(f[4], f[5], w1, false); w1 = __builtin_amdgcn_cvt_pk_fp8_f32(f[6], f[7], w1, true);
;                         w2 = __builtin_amdgcn_cvt_pk_fp8_f32(f[8], f[9], w2, false); w2 = __builtin_amdgcn_cvt_pk_fp8_f32(f[10], f[11], w2, true);
;                         w3 = __builtin_amdgcn_cvt_pk_fp8_f32(f[12], f[13], w3, false); w3 = __builtin_amdgcn_cvt_pk_fp8_f32(f[14], f[15], w3, true);
;                         u32x4 o8; o8.x = (unsigned)w0; o8.y = (unsigned)w1; o8.z = (unsigned)w2; o8.w = (unsigned)w3;
;                         *(u32x4*)(KV8 + (size_t)t * 2048 + lane * 16) = o8;
;                     }
;                 }
;                 {
	v_mov_b32_e32 v40, v148
	v_mov_b32_e32 v41, v149
	v_mov_b32_e32 v42, v150
	v_mov_b32_e32 v43, v151
	s_nop 0
	v_mov_b32_e32 v44, v152
	v_mov_b32_e32 v45, v153
	v_mov_b32_e32 v46, v154
	v_mov_b32_e32 v47, v155
	v_add_co_u32_e32 v52, vcc, s6, v10
	global_store_dwordx4 v[48:49], v[32:35], off offset:2048
	global_store_dwordx4 v[48:49], v[36:39], off offset:2064
	v_addc_co_u32_e32 v53, vcc, 0, v11, vcc
	v_lshl_add_u64 v[8:9], v[8:9], 0, s[4:5]
	v_lshlrev_b32_e32 v10, 16, v40
	v_and_b32_e32 v11, 0xffff0000, v40
	v_lshlrev_b32_e32 v39, 16, v45
	v_and_b32_e32 v40, 0xffff0000, v45
	v_fma_f32 v45, v10, v10, 0
	v_lshlrev_b32_e32 v31, 16, v41
	v_fmac_f32_e32 v45, v11, v11
	v_and_b32_e32 v32, 0xffff0000, v41
	v_fmac_f32_e32 v45, v31, v31
	v_lshlrev_b32_e32 v33, 16, v42
	v_fmac_f32_e32 v45, v32, v32
	v_and_b32_e32 v34, 0xffff0000, v42
	v_fmac_f32_e32 v45, v33, v33
	v_lshlrev_b32_e32 v35, 16, v43
	v_fmac_f32_e32 v45, v34, v34
	v_and_b32_e32 v36, 0xffff0000, v43
	v_fmac_f32_e32 v45, v35, v35
	v_lshlrev_b32_e32 v37, 16, v44
	v_fmac_f32_e32 v45, v36, v36
	v_and_b32_e32 v38, 0xffff0000, v44
	v_fmac_f32_e32 v45, v37, v37
	v_fmac_f32_e32 v45, v38, v38
	v_fmac_f32_e32 v45, v39, v39
	v_lshlrev_b32_e32 v41, 16, v46
	v_fmac_f32_e32 v45, v40, v40
	v_and_b32_e32 v42, 0xffff0000, v46
	v_fmac_f32_e32 v45, v41, v41
	v_lshlrev_b32_e32 v43, 16, v47
	v_fmac_f32_e32 v45, v42, v42
	v_and_b32_e32 v44, 0xffff0000, v47
	v_fmac_f32_e32 v45, v43, v43
	v_fmac_f32_e32 v45, v44, v44
	ds_bpermute_b32 v46, v12, v45
	s_waitcnt lgkmcnt(0)
	v_add_f32_e32 v45, v45, v46
	ds_bpermute_b32 v46, v13, v45
	s_waitcnt lgkmcnt(0)
	v_add_f32_e32 v45, v45, v46
	ds_bpermute_b32 v46, v14, v45
	s_waitcnt lgkmcnt(0)
	v_add_f32_e32 v45, v45, v46
	v_fmamk_f32 v45, v45, 0x3c000000, v121
	v_mul_f32_e32 v46, 0x4f800000, v45
	v_cmp_gt_f32_e32 vcc, s39, v45
	s_nop 1
	v_cndmask_b32_e32 v45, v45, v46, vcc
	v_sqrt_f32_e32 v46, v45
	s_nop 0
	v_add_u32_e32 v47, -1, v46
	v_add_u32_e32 v48, 1, v46
	v_fma_f32 v49, -v47, v46, v45
	v_fma_f32 v54, -v48, v46, v45
	v_cmp_ge_f32_e64 s[6:7], 0, v49
	s_nop 1
	v_cndmask_b32_e64 v46, v46, v47, s[6:7]
	v_cmp_lt_f32_e64 s[6:7], 0, v54
	s_nop 1
	v_cndmask_b32_e64 v46, v46, v48, s[6:7]
	v_mul_f32_e32 v47, 0x37800000, v46
	v_cndmask_b32_e32 v46, v46, v47, vcc
	v_cmp_class_f32_e32 vcc, v45, v122
	s_nop 1
	v_cndmask_b32_e32 v45, v46, v45, vcc
	v_div_scale_f32 v46, s[4:5], v45, v45, 1.0
	v_rcp_f32_e32 v48, v46
	v_div_scale_f32 v47, vcc, 1.0, v45, 1.0
	v_fma_f32 v49, -v46, v48, 1.0
	v_fmac_f32_e32 v48, v49, v48
	v_mul_f32_e32 v49, v47, v48
	v_fma_f32 v54, -v46, v49, v47
	v_fmac_f32_e32 v49, v54, v48
	v_fma_f32 v46, -v46, v49, v47
	v_div_fmas_f32 v46, v46, v48, v49
	v_div_fixup_f32 v45, v46, v45, 1.0
	v_mul_f32_e32 v42, v45, v42
	v_mul_f32_e32 v41, v45, v41
	v_mul_f32_e32 v38, v45, v38
	v_mul_f32_e32 v37, v45, v37
	v_mul_f32_e32 v34, v45, v34
	v_mul_f32_e32 v33, v45, v33
	v_mul_f32_e32 v11, v45, v11
	v_mul_f32_e32 v10, v45, v10
	v_cvt_pk_fp8_f32 v0, v10, v11
	v_cvt_pk_fp8_f32 v1, v33, v34
	v_cvt_pk_fp8_f32 v2, v37, v38
	v_cvt_pk_fp8_f32 v3, v41, v42
	v_mul_f32_e32 v44, v45, v44
	v_mul_f32_e32 v43, v45, v43
	v_mul_f32_e32 v40, v45, v40
	v_mul_f32_e32 v39, v45, v39
	v_mul_f32_e32 v36, v45, v36
	v_mul_f32_e32 v35, v45, v35
	v_mul_f32_e32 v32, v45, v32
	v_mul_f32_e32 v31, v45, v31
	v_cvt_pk_fp8_f32 v0, v31, v32 op_sel:[0,0,1]
	v_cvt_pk_fp8_f32 v1, v35, v36 op_sel:[0,0,1]
	v_cvt_pk_fp8_f32 v2, v39, v40 op_sel:[0,0,1]
	v_cvt_pk_fp8_f32 v3, v43, v44 op_sel:[0,0,1]
	v_mov_b32_e32 v32, 0
	v_mov_b32_e32 v33, 0
	v_mov_b32_e32 v34, 0
	global_store_dwordx4 v[52:53], v[0:3], off
	s_waitcnt vmcnt(3)
	v_mov_b32_e32 v8, v160
	v_mov_b32_e32 v9, v161
	v_mov_b32_e32 v10, v162
	v_mov_b32_e32 v11, v163
	s_nop 0
	v_mov_b32_e32 v0, v156
	v_mov_b32_e32 v1, v157
	v_mov_b32_e32 v2, v158
	v_mov_b32_e32 v3, v159
	v_mov_b32_e32 v35, 0
	v_lshlrev_b32_e32 v31, 16, v0
	v_and_b32_e32 v0, 0xffff0000, v0
	v_lshlrev_b32_e32 v37, 16, v2
	v_and_b32_e32 v2, 0xffff0000, v2
	v_lshlrev_b32_e32 v39, 16, v8
	v_and_b32_e32 v8, 0xffff0000, v8
	v_lshlrev_b32_e32 v41, 16, v10
	v_and_b32_e32 v10, 0xffff0000, v10
	v_cvt_pk_fp8_f32 v32, v31, v0
	v_cvt_pk_fp8_f32 v33, v37, v2
	v_cvt_pk_fp8_f32 v34, v39, v8
	v_cvt_pk_fp8_f32 v35, v41, v10
	v_lshlrev_b32_e32 v36, 16, v1
	v_and_b32_e32 v1, 0xffff0000, v1
	v_lshlrev_b32_e32 v38, 16, v3
	v_and_b32_e32 v3, 0xffff0000, v3
	v_lshlrev_b32_e32 v40, 16, v9
	v_and_b32_e32 v9, 0xffff0000, v9
	v_lshlrev_b32_e32 v42, 16, v11
	v_and_b32_e32 v11, 0xffff0000, v11
	v_cvt_pk_fp8_f32 v32, v36, v1 op_sel:[0,0,1]
	v_cvt_pk_fp8_f32 v33, v38, v3 op_sel:[0,0,1]
	v_cvt_pk_fp8_f32 v34, v40, v9 op_sel:[0,0,1]
	v_cvt_pk_fp8_f32 v35, v42, v11 op_sel:[0,0,1]
	global_store_dwordx4 v[52:53], v[32:35], off offset:1024
	s_cbranch_scc0 .LBB0_1175
	s_branch .LBB0_352
